# P8 K-loop: all LDS-DMA staging issued from the MFMA segments (4+4 per K-tile), load segments are pure ds_read; waits recounted
# speedup vs baseline: 1.0016x; 1.0016x over previous
.LBB0_944:
	ds_read_b128 v[20:23], v196
	ds_read_b128 v[166:169], v196 offset:1024
	ds_read_b128 v[14:17], v196 offset:2048
	ds_read_b128 v[162:165], v196 offset:3072
	ds_read_b128 v[8:11], v197
	ds_read_b128 v[158:161], v197 offset:1024
	ds_read_b128 v[2:5], v197 offset:2048
	ds_read_b128 v[154:157], v197 offset:3072
	s_add_u32 s40, s38, 0xfff80080
	s_addc_u32 s41, s39, -1
	s_cmp_eq_u32 s64, 28
	s_cselect_b32 s43, s23, s41
	s_cselect_b32 s42, s60, s40
	s_cselect_b32 s41, s21, s63
	s_cselect_b32 s40, s61, s62
	s_add_u32 s94, s38, 0xfff80000
	s_addc_u32 s95, s39, -1
	ds_read_b128 v[186:189], v198
	ds_read_b128 v[190:193], v198 offset:1024
	ds_read_b128 v[200:203], v198 offset:2048
	ds_read_b128 v[216:219], v198 offset:3072
	ds_read_b128 v[206:209], v198 offset:4096
	ds_read_b128 v[220:223], v198 offset:5120
	ds_read_b128 v[212:215], v198 offset:6144
	ds_read_b128 v[224:227], v198 offset:7168
	v_lshl_add_u64 v[238:239], s[94:95], 0, v[178:179]
	v_lshl_add_u64 v[240:241], s[94:95], 0, v[180:181]
	v_lshl_add_u64 v[242:243], s[38:39], 0, v[178:179]
	v_lshl_add_u64 v[244:245], s[38:39], 0, v[180:181]
	s_waitcnt vmcnt(4)
	s_waitcnt lgkmcnt(0)
	s_barrier
	s_setprio 1
	s_waitcnt lgkmcnt(0)
	v_mov_b32_e32 v24, v166
	v_mov_b32_e32 v25, v167
	s_nop 1
	v_mfma_scale_f32_16x16x128_f8f6f4 v[150:153], v[20:25], v[186:191], v[150:153], v168, v192 op_sel_hi:[0,0,0] cbsz:2 blgp:2
	s_mov_b32 m0, s53
	s_nop 0
	global_load_lds_dwordx4 v[238:239], off
	v_mov_b32_e32 v18, v162
	v_mov_b32_e32 v19, v163
	s_nop 1
	v_mfma_scale_f32_16x16x128_f8f6f4 v[146:149], v[14:19], v[186:191], v[146:149], v164, v192 op_sel_hi:[0,0,0] cbsz:2 blgp:2
	v_mov_b32_e32 v204, v216
	v_mov_b32_e32 v205, v217
	s_nop 1
	v_mfma_scale_f32_16x16x128_f8f6f4 v[142:145], v[20:25], v[200:205], v[142:145], v168, v218 op_sel_hi:[0,0,0] cbsz:2 blgp:2
	s_nop 1
	v_mfma_scale_f32_16x16x128_f8f6f4 v[138:141], v[14:19], v[200:205], v[138:141], v164, v218 op_sel_hi:[0,0,0] cbsz:2 blgp:2
	v_mov_b32_e32 v210, v220
	v_mov_b32_e32 v211, v221
	s_nop 1
	v_mfma_scale_f32_16x16x128_f8f6f4 v[134:137], v[20:25], v[206:211], v[134:137], v168, v222 op_sel_hi:[0,0,0] cbsz:2 blgp:2
	s_mov_b32 m0, s54
	s_nop 0
	global_load_lds_dwordx4 v[240:241], off
	s_nop 1
	v_mfma_scale_f32_16x16x128_f8f6f4 v[130:133], v[14:19], v[206:211], v[130:133], v164, v222 op_sel_hi:[0,0,0] cbsz:2 blgp:2
	v_mov_b32_e32 v216, v224
	v_mov_b32_e32 v217, v225
	s_nop 1
	v_mfma_scale_f32_16x16x128_f8f6f4 v[126:129], v[20:25], v[212:217], v[126:129], v168, v226 op_sel_hi:[0,0,0] cbsz:2 blgp:2
	s_nop 1
	v_mfma_scale_f32_16x16x128_f8f6f4 v[122:125], v[14:19], v[212:217], v[122:125], v164, v226 op_sel_hi:[0,0,0] cbsz:2 blgp:2
	s_setprio 0
	s_setprio 1
	v_mov_b32_e32 v12, v158
	v_mov_b32_e32 v13, v159
	s_nop 1
	v_mfma_scale_f32_16x16x128_f8f6f4 v[118:121], v[8:13], v[186:191], v[118:121], v160, v192 op_sel_hi:[0,0,0] cbsz:2 blgp:2
	s_add_i32 m0, s37, 0xc000
	s_nop 0
	global_load_lds_dwordx4 v[242:243], off
	v_mov_b32_e32 v6, v154
	v_mov_b32_e32 v7, v155
	s_nop 1
	v_mfma_scale_f32_16x16x128_f8f6f4 v[114:117], v[2:7], v[186:191], v[114:117], v156, v192 op_sel_hi:[0,0,0] cbsz:2 blgp:2
	s_nop 1
	v_mfma_scale_f32_16x16x128_f8f6f4 v[110:113], v[8:13], v[200:205], v[110:113], v160, v218 op_sel_hi:[0,0,0] cbsz:2 blgp:2
	s_nop 1
	v_mfma_scale_f32_16x16x128_f8f6f4 v[106:109], v[2:7], v[200:205], v[106:109], v156, v218 op_sel_hi:[0,0,0] cbsz:2 blgp:2
	s_nop 1
	v_mfma_scale_f32_16x16x128_f8f6f4 v[102:105], v[8:13], v[206:211], v[102:105], v160, v222 op_sel_hi:[0,0,0] cbsz:2 blgp:2
	s_add_i32 m0, s37, 0xe000
	s_nop 0
	global_load_lds_dwordx4 v[244:245], off
	s_nop 1
	v_mfma_scale_f32_16x16x128_f8f6f4 v[98:101], v[2:7], v[206:211], v[98:101], v156, v222 op_sel_hi:[0,0,0] cbsz:2 blgp:2
	s_nop 1
	v_mfma_scale_f32_16x16x128_f8f6f4 v[94:97], v[8:13], v[212:217], v[94:97], v160, v226 op_sel_hi:[0,0,0] cbsz:2 blgp:2
	s_nop 1
	v_mfma_scale_f32_16x16x128_f8f6f4 v[90:93], v[2:7], v[212:217], v[90:93], v156, v226 op_sel_hi:[0,0,0] cbsz:2 blgp:2
	s_setprio 0
	s_barrier
	s_add_u32 s44, s40, 0x80000
	s_addc_u32 s45, s41, 0
	ds_read_b128 v[200:203], v198 offset:16384
	ds_read_b128 v[222:225], v198 offset:17408
	ds_read_b128 v[206:209], v198 offset:18432
	ds_read_b128 v[226:229], v198 offset:19456
	ds_read_b128 v[212:215], v198 offset:20480
	ds_read_b128 v[230:233], v198 offset:21504
	ds_read_b128 v[218:221], v198 offset:22528
	ds_read_b128 v[234:237], v198 offset:23552
	v_lshl_add_u64 v[186:187], s[40:41], 0, v[174:175]
	v_lshl_add_u64 v[188:189], s[40:41], 0, v[170:171]
	v_lshl_add_u64 v[190:191], s[42:43], 0, v[176:177]
	v_lshl_add_u64 v[192:193], s[42:43], 0, v[172:173]
	v_lshl_add_u64 v[238:239], s[44:45], 0, v[174:175]
	v_lshl_add_u64 v[240:241], s[44:45], 0, v[170:171]
	s_waitcnt vmcnt(2)
	s_waitcnt lgkmcnt(0)
	s_barrier
	s_setprio 1
	s_waitcnt lgkmcnt(0)
	v_mov_b32_e32 v204, v222
	v_mov_b32_e32 v205, v223
	s_nop 1
	v_mfma_scale_f32_16x16x128_f8f6f4 v[86:89], v[20:25], v[200:205], v[86:89], v168, v224 op_sel_hi:[0,0,0] cbsz:2 blgp:2
	s_add_i32 m0, s37, 0x10000
	s_nop 0
	global_load_lds_dwordx4 v[186:187], off
	s_nop 1
	v_mfma_scale_f32_16x16x128_f8f6f4 v[82:85], v[14:19], v[200:205], v[82:85], v164, v224 op_sel_hi:[0,0,0] cbsz:2 blgp:2
	v_mov_b32_e32 v210, v226
	v_mov_b32_e32 v211, v227
	s_nop 1
	v_mfma_scale_f32_16x16x128_f8f6f4 v[78:81], v[20:25], v[206:211], v[78:81], v168, v228 op_sel_hi:[0,0,0] cbsz:2 blgp:2
	s_nop 1
	v_mfma_scale_f32_16x16x128_f8f6f4 v[74:77], v[14:19], v[206:211], v[74:77], v164, v228 op_sel_hi:[0,0,0] cbsz:2 blgp:2
	v_mov_b32_e32 v216, v230
	v_mov_b32_e32 v217, v231
	s_nop 1
	v_mfma_scale_f32_16x16x128_f8f6f4 v[70:73], v[20:25], v[212:217], v[70:73], v168, v232 op_sel_hi:[0,0,0] cbsz:2 blgp:2
	s_add_i32 m0, s37, 0x12000
	s_nop 0
	global_load_lds_dwordx4 v[188:189], off
	s_nop 1
	v_mfma_scale_f32_16x16x128_f8f6f4 v[66:69], v[14:19], v[212:217], v[66:69], v164, v232 op_sel_hi:[0,0,0] cbsz:2 blgp:2
	v_mov_b32_e32 v222, v234
	v_mov_b32_e32 v223, v235
	s_nop 1
	v_mfma_scale_f32_16x16x128_f8f6f4 v[62:65], v[20:25], v[218:223], v[62:65], v168, v236 op_sel_hi:[0,0,0] cbsz:2 blgp:2
	s_nop 1
	v_mfma_scale_f32_16x16x128_f8f6f4 v[58:61], v[14:19], v[218:223], v[58:61], v164, v236 op_sel_hi:[0,0,0] cbsz:2 blgp:2
	s_setprio 0
	s_setprio 1
	s_nop 1
	v_mfma_scale_f32_16x16x128_f8f6f4 v[54:57], v[8:13], v[200:205], v[54:57], v160, v224 op_sel_hi:[0,0,0] cbsz:2 blgp:2
	s_add_i32 m0, s37, 0x14000
	s_nop 0
	global_load_lds_dwordx4 v[238:239], off
	s_nop 1
	v_mfma_scale_f32_16x16x128_f8f6f4 v[50:53], v[2:7], v[200:205], v[50:53], v156, v224 op_sel_hi:[0,0,0] cbsz:2 blgp:2
	s_nop 1
	v_mfma_scale_f32_16x16x128_f8f6f4 v[46:49], v[8:13], v[206:211], v[46:49], v160, v228 op_sel_hi:[0,0,0] cbsz:2 blgp:2
	s_nop 1
	v_mfma_scale_f32_16x16x128_f8f6f4 v[42:45], v[2:7], v[206:211], v[42:45], v156, v228 op_sel_hi:[0,0,0] cbsz:2 blgp:2
	s_nop 1
	v_mfma_scale_f32_16x16x128_f8f6f4 v[38:41], v[8:13], v[212:217], v[38:41], v160, v232 op_sel_hi:[0,0,0] cbsz:2 blgp:2
	s_add_i32 m0, s37, 0x16000
	s_nop 0
	global_load_lds_dwordx4 v[240:241], off
	s_nop 1
	v_mfma_scale_f32_16x16x128_f8f6f4 v[34:37], v[2:7], v[212:217], v[34:37], v156, v232 op_sel_hi:[0,0,0] cbsz:2 blgp:2
	s_nop 1
	v_mfma_scale_f32_16x16x128_f8f6f4 v[30:33], v[8:13], v[218:223], v[30:33], v160, v236 op_sel_hi:[0,0,0] cbsz:2 blgp:2
	s_nop 1
	v_mfma_scale_f32_16x16x128_f8f6f4 v[26:29], v[2:7], v[218:223], v[26:29], v156, v236 op_sel_hi:[0,0,0] cbsz:2 blgp:2
	s_setprio 0
	s_barrier
	s_add_i32 s44, 0, 0x18000
	s_add_i32 s45, 0, 0x1c000
	v_add_u32_e32 v2, s44, v1
	v_add_u32_e32 v6, s45, v1
	ds_read_b128 v[20:23], v2
	ds_read_b128 v[166:169], v2 offset:1024
	ds_read_b128 v[14:17], v2 offset:2048
	ds_read_b128 v[162:165], v2 offset:3072
	ds_read_b128 v[8:11], v6
	ds_read_b128 v[154:157], v6 offset:1024
	ds_read_b128 v[2:5], v6 offset:2048
	ds_read_b128 v[158:161], v6 offset:3072
	s_add_u32 s42, s42, 0x80000
	s_addc_u32 s43, s43, 0
	v_lshl_add_u64 v[238:239], s[42:43], 0, v[176:177]
	ds_read_b128 v[200:203], v198 offset:32768
	ds_read_b128 v[222:225], v198 offset:33792
	ds_read_b128 v[206:209], v198 offset:34816
	ds_read_b128 v[226:229], v198 offset:35840
	ds_read_b128 v[212:215], v198 offset:36864
	ds_read_b128 v[230:233], v198 offset:37888
	ds_read_b128 v[218:221], v198 offset:38912
	ds_read_b128 v[234:237], v198 offset:39936
	v_lshl_add_u64 v[240:241], s[42:43], 0, v[172:173]
	s_waitcnt vmcnt(4)
	s_waitcnt lgkmcnt(0)
	s_barrier
	s_setprio 1
	s_waitcnt lgkmcnt(0)
	v_mov_b32_e32 v204, v222
	v_mov_b32_e32 v205, v223
	v_mov_b32_e32 v24, v166
	v_mov_b32_e32 v25, v167
	s_nop 1
	v_mfma_scale_f32_16x16x128_f8f6f4 v[150:153], v[20:25], v[200:205], v[150:153], v168, v224 op_sel_hi:[0,0,0] cbsz:2 blgp:2
	s_mov_b32 m0, s37
	s_nop 0
	global_load_lds_dwordx4 v[190:191], off
	v_mov_b32_e32 v18, v162
	v_mov_b32_e32 v19, v163
	s_nop 1
	v_mfma_scale_f32_16x16x128_f8f6f4 v[146:149], v[14:19], v[200:205], v[146:149], v164, v224 op_sel_hi:[0,0,0] cbsz:2 blgp:2
	v_mov_b32_e32 v210, v226
	v_mov_b32_e32 v211, v227
	s_nop 1
	v_mfma_scale_f32_16x16x128_f8f6f4 v[142:145], v[20:25], v[206:211], v[142:145], v168, v228 op_sel_hi:[0,0,0] cbsz:2 blgp:2
	s_nop 1
	v_mfma_scale_f32_16x16x128_f8f6f4 v[138:141], v[14:19], v[206:211], v[138:141], v164, v228 op_sel_hi:[0,0,0] cbsz:2 blgp:2
	v_mov_b32_e32 v216, v230
	v_mov_b32_e32 v217, v231
	s_nop 1
	v_mfma_scale_f32_16x16x128_f8f6f4 v[134:137], v[20:25], v[212:217], v[134:137], v168, v232 op_sel_hi:[0,0,0] cbsz:2 blgp:2
	s_mov_b32 m0, s48
	s_nop 0
	global_load_lds_dwordx4 v[192:193], off
	s_nop 1
	v_mfma_scale_f32_16x16x128_f8f6f4 v[130:133], v[14:19], v[212:217], v[130:133], v164, v232 op_sel_hi:[0,0,0] cbsz:2 blgp:2
	v_mov_b32_e32 v222, v234
	v_mov_b32_e32 v223, v235
	s_nop 1
	v_mfma_scale_f32_16x16x128_f8f6f4 v[126:129], v[20:25], v[218:223], v[126:129], v168, v236 op_sel_hi:[0,0,0] cbsz:2 blgp:2
	s_nop 1
	v_mfma_scale_f32_16x16x128_f8f6f4 v[122:125], v[14:19], v[218:223], v[122:125], v164, v236 op_sel_hi:[0,0,0] cbsz:2 blgp:2
	s_setprio 0
	s_setprio 1
	v_mov_b32_e32 v12, v154
	v_mov_b32_e32 v13, v155
	s_nop 1
	v_mfma_scale_f32_16x16x128_f8f6f4 v[118:121], v[8:13], v[200:205], v[118:121], v156, v224 op_sel_hi:[0,0,0] cbsz:2 blgp:2
	s_mov_b32 m0, s49
	s_nop 0
	global_load_lds_dwordx4 v[238:239], off
	v_mov_b32_e32 v6, v158
	v_mov_b32_e32 v7, v159
	s_nop 1
	v_mfma_scale_f32_16x16x128_f8f6f4 v[114:117], v[2:7], v[200:205], v[114:117], v160, v224 op_sel_hi:[0,0,0] cbsz:2 blgp:2
	s_nop 1
	v_mfma_scale_f32_16x16x128_f8f6f4 v[110:113], v[8:13], v[206:211], v[110:113], v156, v228 op_sel_hi:[0,0,0] cbsz:2 blgp:2
	s_nop 1
	v_mfma_scale_f32_16x16x128_f8f6f4 v[106:109], v[2:7], v[206:211], v[106:109], v160, v228 op_sel_hi:[0,0,0] cbsz:2 blgp:2
	s_nop 1
	v_mfma_scale_f32_16x16x128_f8f6f4 v[102:105], v[8:13], v[212:217], v[102:105], v156, v232 op_sel_hi:[0,0,0] cbsz:2 blgp:2
	s_mov_b32 m0, s50
	s_nop 0
	global_load_lds_dwordx4 v[240:241], off
	s_nop 1
	v_mfma_scale_f32_16x16x128_f8f6f4 v[98:101], v[2:7], v[212:217], v[98:101], v160, v232 op_sel_hi:[0,0,0] cbsz:2 blgp:2
	s_nop 1
	v_mfma_scale_f32_16x16x128_f8f6f4 v[94:97], v[8:13], v[218:223], v[94:97], v156, v236 op_sel_hi:[0,0,0] cbsz:2 blgp:2
	s_nop 1
	v_mfma_scale_f32_16x16x128_f8f6f4 v[90:93], v[2:7], v[218:223], v[90:93], v160, v236 op_sel_hi:[0,0,0] cbsz:2 blgp:2
	s_setprio 0
	s_barrier
	s_add_u32 s40, s40, 0x80080
	s_addc_u32 s41, s41, 0
	ds_read_b128 v[200:203], v198 offset:49152
	ds_read_b128 v[222:225], v198 offset:50176
	ds_read_b128 v[206:209], v198 offset:51200
	ds_read_b128 v[226:229], v198 offset:52224
	ds_read_b128 v[212:215], v198 offset:53248
	ds_read_b128 v[230:233], v198 offset:54272
	ds_read_b128 v[218:221], v198 offset:55296
	ds_read_b128 v[234:237], v198 offset:56320
	v_lshl_add_u64 v[238:239], v[186:187], 0, s[12:13]
	v_lshl_add_u64 v[240:241], v[188:189], 0, s[12:13]
	v_lshl_add_u64 v[242:243], s[40:41], 0, v[174:175]
	v_lshl_add_u64 v[244:245], s[40:41], 0, v[170:171]
	s_waitcnt vmcnt(2)
	s_waitcnt lgkmcnt(0)
	s_barrier
	s_setprio 1
	s_waitcnt lgkmcnt(0)
	v_mov_b32_e32 v204, v222
	v_mov_b32_e32 v205, v223
	s_nop 1
	v_mfma_scale_f32_16x16x128_f8f6f4 v[86:89], v[20:25], v[200:205], v[86:89], v168, v224 op_sel_hi:[0,0,0] cbsz:2 blgp:2
	s_add_i32 m0, s37, 0x18000
	s_nop 0
	global_load_lds_dwordx4 v[238:239], off
	s_nop 1
	v_mfma_scale_f32_16x16x128_f8f6f4 v[82:85], v[14:19], v[200:205], v[82:85], v164, v224 op_sel_hi:[0,0,0] cbsz:2 blgp:2
	v_mov_b32_e32 v210, v226
	v_mov_b32_e32 v211, v227
	s_nop 1
	v_mfma_scale_f32_16x16x128_f8f6f4 v[78:81], v[20:25], v[206:211], v[78:81], v168, v228 op_sel_hi:[0,0,0] cbsz:2 blgp:2
	s_nop 1
	v_mfma_scale_f32_16x16x128_f8f6f4 v[74:77], v[14:19], v[206:211], v[74:77], v164, v228 op_sel_hi:[0,0,0] cbsz:2 blgp:2
	v_mov_b32_e32 v216, v230
	v_mov_b32_e32 v217, v231
	s_nop 1
	v_mfma_scale_f32_16x16x128_f8f6f4 v[70:73], v[20:25], v[212:217], v[70:73], v168, v232 op_sel_hi:[0,0,0] cbsz:2 blgp:2
	s_add_i32 m0, s37, 0x1a000
	s_nop 0
	global_load_lds_dwordx4 v[240:241], off
	s_nop 1
	v_mfma_scale_f32_16x16x128_f8f6f4 v[66:69], v[14:19], v[212:217], v[66:69], v164, v232 op_sel_hi:[0,0,0] cbsz:2 blgp:2
	v_mov_b32_e32 v222, v234
	v_mov_b32_e32 v223, v235
	s_nop 1
	v_mfma_scale_f32_16x16x128_f8f6f4 v[62:65], v[20:25], v[218:223], v[62:65], v168, v236 op_sel_hi:[0,0,0] cbsz:2 blgp:2
	s_nop 1
	v_mfma_scale_f32_16x16x128_f8f6f4 v[58:61], v[14:19], v[218:223], v[58:61], v164, v236 op_sel_hi:[0,0,0] cbsz:2 blgp:2
	s_setprio 0
	s_setprio 1
	s_nop 1
	v_mfma_scale_f32_16x16x128_f8f6f4 v[54:57], v[8:13], v[200:205], v[54:57], v156, v224 op_sel_hi:[0,0,0] cbsz:2 blgp:2
	s_add_i32 m0, s37, 0x1c000
	s_nop 0
	global_load_lds_dwordx4 v[242:243], off
	s_nop 1
	v_mfma_scale_f32_16x16x128_f8f6f4 v[50:53], v[2:7], v[200:205], v[50:53], v160, v224 op_sel_hi:[0,0,0] cbsz:2 blgp:2
	s_nop 1
	v_mfma_scale_f32_16x16x128_f8f6f4 v[46:49], v[8:13], v[206:211], v[46:49], v156, v228 op_sel_hi:[0,0,0] cbsz:2 blgp:2
	s_nop 1
	v_mfma_scale_f32_16x16x128_f8f6f4 v[42:45], v[2:7], v[206:211], v[42:45], v160, v228 op_sel_hi:[0,0,0] cbsz:2 blgp:2
	s_nop 1
	v_mfma_scale_f32_16x16x128_f8f6f4 v[38:41], v[8:13], v[212:217], v[38:41], v156, v232 op_sel_hi:[0,0,0] cbsz:2 blgp:2
	s_add_i32 m0, s37, 0x1e000
	s_nop 0
	global_load_lds_dwordx4 v[244:245], off
	s_nop 1
	v_mfma_scale_f32_16x16x128_f8f6f4 v[34:37], v[2:7], v[212:217], v[34:37], v160, v232 op_sel_hi:[0,0,0] cbsz:2 blgp:2
	s_nop 1
	v_mfma_scale_f32_16x16x128_f8f6f4 v[30:33], v[8:13], v[218:223], v[30:33], v156, v236 op_sel_hi:[0,0,0] cbsz:2 blgp:2
	s_nop 1
	v_mfma_scale_f32_16x16x128_f8f6f4 v[26:29], v[2:7], v[218:223], v[26:29], v160, v236 op_sel_hi:[0,0,0] cbsz:2 blgp:2
	s_setprio 0
	s_barrier
	s_add_i32 s64, s64, 2
	s_add_u32 s38, s38, 0x100
	s_addc_u32 s39, s39, 0
	s_add_u32 s62, s62, 0x100
	s_addc_u32 s63, s63, 0
	s_cmp_lt_u32 s64, 30
	s_cbranch_scc1 .LBB0_944
	s_nop 15
	s_nop 15
	s_andn2_b64 vcc, exec, s[14:15]
	s_cbranch_vccnz .LBB0_947
	s_barrier
